# XCD-local release for the 4 row-panel-local GEMM->GEMM grid barriers per layer (leader skips L2 write-back and cross-XCD top stage when each blockIdx%8 class sits on its own XCD, checked at run time)
# speedup vs baseline: 1.0054x; 1.0052x over previous
; #define LAS __attribute__((address_space(3)))
; DEVI unsigned xb_add(unsigned* p, unsigned v) { return __hip_atomic_fetch_add(p, v, __ATOMIC_RELAXED, __HIP_MEMORY_SCOPE_AGENT); }
; DEVI unsigned xb_xcc_id() { return (unsigned)__builtin_amdgcn_s_getreg((3 << 11) | 20) & 0xFu; }
; DEVI XcdBarrier xcd_barrier_post(unsigned* bar, volatile LAS unsigned* st) {
;     XcdBarrier b; b.bar = bar; b.x = xb_xcc_id(); b.st = st;
;     if (threadIdx.x == 0) (void)xb_add(&bar[XB_XCNT(b.x)], 1u);
;     return b;
; }
; __global__ void __launch_bounds__(512, 2) fwd_megakernel(Params p) {
;     extern __shared__ __attribute__((aligned(16))) unsigned char smem[];
;     cg::grid_group grid = cg::this_grid();
;     LAS unsigned char* lds = (LAS unsigned char*)smem;
;     unsigned char* ws = p.ws;
;     u16* HN = (u16*)(ws + OFF_HN); u16* PROJ = (u16*)(ws + OFF_PROJ); float* GATES = (float*)(ws + OFF_GATES);
;     float* H = p.out;
;     unsigned* bar = (unsigned*)(ws + OFF_BAR);
;     volatile LAS unsigned* st = (volatile LAS unsigned*)(lds + LDS_MAIN);
;     if (blockIdx.x == 0) for (int i = threadIdx.x; i < XCD_BAR_WORDS; i += 512) bar[i] = 0u;
;     if (threadIdx.x == 0) { st[0] = 0u; st[1] = 0u; }
;     grid.sync();
;     const XcdBarrier xb = xcd_barrier_post(bar, st);
.LBB0_20:
	s_or_b64 exec, exec, s[8:9]
	s_load_dwordx16 s[36:51], s[0:1], 0x0
	s_load_dwordx16 s[60:75], s[0:1], 0x80
	s_load_dwordx16 s[4:19], s[0:1], 0xc0
	s_barrier
	s_waitcnt lgkmcnt(0)
	v_writelane_b32 v251, s36, 8
	s_nop 1
	v_writelane_b32 v251, s37, 9
	v_writelane_b32 v251, s38, 10
	v_writelane_b32 v251, s39, 11
	v_writelane_b32 v251, s40, 12
	v_writelane_b32 v251, s41, 13
	v_writelane_b32 v251, s42, 14
	v_writelane_b32 v251, s43, 15
	v_writelane_b32 v251, s44, 16
	v_writelane_b32 v251, s45, 17
	v_writelane_b32 v251, s46, 18
	v_writelane_b32 v251, s47, 19
	v_writelane_b32 v251, s48, 20
	v_writelane_b32 v251, s49, 21
	v_writelane_b32 v251, s50, 22
	v_writelane_b32 v251, s51, 23
	s_load_dwordx16 s[36:51], s[0:1], 0x40
	s_getreg_b32 s0, hwreg(HW_REG_XCC_ID, 0, 4)
	s_and_b32 s81, s0, 15
	s_waitcnt lgkmcnt(0)
	v_writelane_b32 v251, s36, 24
	s_nop 1
	v_writelane_b32 v251, s37, 25
	v_writelane_b32 v251, s38, 26
	v_writelane_b32 v251, s39, 27
	v_writelane_b32 v251, s40, 28
	v_writelane_b32 v251, s41, 29
	v_writelane_b32 v251, s42, 30
	v_writelane_b32 v251, s43, 31
	v_writelane_b32 v251, s44, 32
	v_writelane_b32 v251, s45, 33
	v_writelane_b32 v251, s46, 34
	v_writelane_b32 v251, s47, 35
	v_writelane_b32 v251, s48, 36
	v_writelane_b32 v251, s49, 37
	v_writelane_b32 v251, s50, 38
	v_writelane_b32 v251, s51, 39
	v_writelane_b32 v251, s4, 40
	s_nop 1
	v_writelane_b32 v251, s5, 41
	v_writelane_b32 v251, s6, 42
	v_writelane_b32 v251, s7, 43
	v_writelane_b32 v251, s8, 44
	v_writelane_b32 v251, s9, 45
	v_writelane_b32 v251, s10, 46
	v_writelane_b32 v251, s11, 47
	v_writelane_b32 v251, s12, 48
	v_writelane_b32 v251, s13, 49
	v_writelane_b32 v251, s14, 50
	v_writelane_b32 v251, s15, 51
	v_writelane_b32 v251, s16, 52
	v_writelane_b32 v251, s17, 53
	v_writelane_b32 v251, s18, 54
	v_writelane_b32 v251, s19, 55
	s_mov_b64 s[0:1], exec
	v_readlane_b32 s4, v251, 6
	v_readlane_b32 s5, v251, 7
	s_and_b64 s[4:5], s[0:1], s[4:5]
	s_mov_b64 exec, s[4:5]
	s_cbranch_execz .LBB0_23
	s_mov_b64 s[4:5], exec
	v_mbcnt_lo_u32_b32 v0, s4, 0
	v_mbcnt_hi_u32_b32 v0, s5, v0
	v_cmp_eq_u32_e32 vcc, 0, v0
	s_and_b64 s[8:9], exec, vcc
	s_mov_b64 exec, s[8:9]
	s_cbranch_execz .LBB0_23
	s_lshl_b32 s8, s81, 8
	s_bcnt1_i32_b64 s4, s[4:5]
	v_readlane_b32 s2, v251, 2
	v_mov_b32_e32 v0, s8
	v_mov_b32_e32 v1, s4
	v_readlane_b32 s3, v251, 3
	s_nop 4
	global_atomic_add v0, v1, s[2:3] offset:1024
	s_and_b32 s4, s33, 7
	s_lshl_b32 s4, s4, 8
	s_lshl_b32 s8, 1, s81
	v_mov_b32_e32 v0, s4
	v_mov_b32_e32 v1, s8
	s_nop 0
	global_atomic_or v0, v1, s[2:3] offset:1088

; DEVI int obid() { int t = blockIdx.x; asm volatile("" : "+s"(t)); return t; }
; DEVI bool unit_next(const Gemm& g, int i, Unit& u) {
;     const int nwg = g.nM * g.nN; int cc = obid() - g.wg_off; if (cc < 0) cc += gridDim.x; const long L = (long)i * gridDim.x + cc;
;     if (L >= (long)nwg * g.nB) return false;
;     u.b = (int)(L / nwg); int wgid = (int)(L % nwg);
;     { const int q = nwg / NXCD, r = nwg % NXCD, xcd = wgid % NXCD, off = wgid / NXCD; wgid = (xcd < r ? xcd * (q + 1) : r * (q + 1) + (xcd - r) * q) + off; }
;     const int nig = WGM * g.nN, gid = wgid / nig, fm = gid * WGM, gsz = (g.nM - fm) < WGM ? (g.nM - fm) : WGM;
;     u.pm = fm + ((wgid % nig) % gsz); u.pn = (wgid % nig) / gsz; return true;
; __global__ void __launch_bounds__(512, 2) fwd_megakernel(Params p) {
;     ...
;     xcd_barrier(xb);
;     { Gemm g{(const u16*)(ws + OFF_MEMN), (const u16*)(ws + OFF_W_XKV), 1024, 1024, 1024, 4, 8, 4, 0, 2048ull * 1024};
;       gemm_phase(lds, g, EpiKV{(u16*)(ws + OFF_KBUF), (u16*)(ws + OFF_VT)}); }
.LBB0_170:
	s_or_b64 exec, exec, s[0:1]
	s_add_u32 s0, s20, 0x8380000
	v_writelane_b32 v252, s0, 36
	s_addc_u32 s0, s21, 0
	v_writelane_b32 v252, s0, 37
	s_add_u32 s0, s20, 0x8b80000
	v_writelane_b32 v252, s0, 38
	s_addc_u32 s0, s21, 0
	v_writelane_b32 v252, s0, 39
	v_mov_b32_e32 v8, v154
	s_mov_b32 s0, s33
	s_waitcnt lgkmcnt(0)
	s_barrier
	v_and_b32_e32 v1, 7, v154
	v_lshlrev_b32_e32 v1, 8, v1
	v_readlane_b32 s2, v251, 2
	v_readlane_b32 s3, v251, 3
	s_nop 4
	global_load_dword v0, v1, s[2:3] offset:1088 sc1
	s_mov_b32 s4, 0
	s_mov_b32 s5, 1
	s_waitcnt vmcnt(0)
	v_readlane_b32 s7, v0, 0
	s_nop 0
	s_or_b32 s4, s4, s7
	s_bcnt1_i32_b32 s8, s7
	s_cmp_eq_u32 s8, 1
	s_cselect_b32 s5, s5, 0
	v_readlane_b32 s7, v0, 1
	s_nop 0
	s_or_b32 s4, s4, s7
	s_bcnt1_i32_b32 s8, s7
	s_cmp_eq_u32 s8, 1
	s_cselect_b32 s5, s5, 0
	v_readlane_b32 s7, v0, 2
	s_nop 0
	s_or_b32 s4, s4, s7
	s_bcnt1_i32_b32 s8, s7
	s_cmp_eq_u32 s8, 1
	s_cselect_b32 s5, s5, 0
	v_readlane_b32 s7, v0, 3
	s_nop 0
	s_or_b32 s4, s4, s7
	s_bcnt1_i32_b32 s8, s7
	s_cmp_eq_u32 s8, 1
	s_cselect_b32 s5, s5, 0
	v_readlane_b32 s7, v0, 4
	s_nop 0
	s_or_b32 s4, s4, s7
	s_bcnt1_i32_b32 s8, s7
	s_cmp_eq_u32 s8, 1
	s_cselect_b32 s5, s5, 0
	v_readlane_b32 s7, v0, 5
	s_nop 0
	s_or_b32 s4, s4, s7
	s_bcnt1_i32_b32 s8, s7
	s_cmp_eq_u32 s8, 1
	s_cselect_b32 s5, s5, 0
	v_readlane_b32 s7, v0, 6
	s_nop 0
	s_or_b32 s4, s4, s7
	s_bcnt1_i32_b32 s8, s7
	s_cmp_eq_u32 s8, 1
	s_cselect_b32 s5, s5, 0
	v_readlane_b32 s7, v0, 7
	s_nop 0
	s_or_b32 s4, s4, s7
	s_bcnt1_i32_b32 s8, s7
	s_cmp_eq_u32 s8, 1
	s_cselect_b32 s5, s5, 0
	s_cmp_eq_u32 s4, 0xff
	s_cselect_b32 s5, s5, 0
	v_mov_b32_e32 v0, s5
	v_mov_b32_e32 v1, 0x26008
	ds_write_b32 v1, v0
	s_waitcnt lgkmcnt(0)
	s_ashr_i32 s1, s0, 31
	s_and_b32 s1, s1, s22
	s_add_i32 s0, s1, s0
	s_cmpk_gt_i32 s0, 0x7f
	v_readfirstlane_b32 s34, v8
	s_cbranch_scc1 .LBB0_192
	s_ashr_i32 s1, s0, 31
	s_lshr_b32 s1, s1, 27
	s_add_i32 s8, s0, s1
	s_and_b32 s1, s8, 0xffe0
	s_sub_i32 s0, s0, s1
	s_bfe_i32 s1, s0, 0x80000
	s_bfe_u32 s1, s1, 0x3000c
	s_add_i32 s1, s0, s1
	s_bfe_i32 s4, s1, 0x80000
	s_and_b32 s1, s1, 0xf8
	s_sub_i32 s0, s0, s1
	s_bfe_i32 s5, s0, 0x80000
	s_sext_i32_i16 s0, s5
	s_cmp_gt_i32 s0, -1
	s_sext_i32_i16 s9, s4
	s_cbranch_scc0 .LBB0_173
	s_lshl_b32 s4, s5, 2
	s_ashr_i32 s10, s8, 5
	s_lshr_b32 s0, s9, 3
	s_cbranch_execz .LBB0_174
	s_branch .LBB0_175

; DEVI unsigned xb_ld(unsigned* p)              { return __hip_atomic_load(p, __ATOMIC_RELAXED, __HIP_MEMORY_SCOPE_AGENT); }
; DEVI unsigned xb_add(unsigned* p, unsigned v) { return __hip_atomic_fetch_add(p, v, __ATOMIC_RELAXED, __HIP_MEMORY_SCOPE_AGENT); }
; #define XB_SPIN(cond, bar) do { unsigned _sp = 0; while (cond) { __builtin_amdgcn_s_sleep(1); \
;     if ((++_sp & 255u) == 0u) { if (xb_ld(&(bar)[XB_TMO])) break; if (_sp > XB_SPIN_CAP) { atomicAdd(&(bar)[XB_TMO], 1u); break; } } } } while (0)
; DEVI void xcd_barrier(const XcdBarrier& b) {
;     ...
;         const unsigned old = xb_add(&bar[XB_XSUB(b.x)], 1u);
;         const unsigned gen = old / nloc;
;         if (old + 1u == (gen + 1u) * nloc) {
;             __builtin_amdgcn_fence(__ATOMIC_RELEASE, "agent");
;             asm volatile("s_waitcnt vmcnt(0)" ::: "memory");
;             const unsigned og = xb_add(&bar[XB_TOP], 1u);
;             const unsigned tg = og / nx;
;             if (og + 1u == (tg + 1u) * nx) xb_add(&bar[XB_TOPGEN], 1u);
;             else XB_SPIN(xb_ld(&bar[XB_TOPGEN]) == tg, bar);
;             __builtin_amdgcn_fence(__ATOMIC_ACQUIRE, "agent");
;             xb_add(&bar[XB_XGEN(b.x)], 1u);
;             asm volatile("s_waitcnt vmcnt(0)" ::: "memory");
.LBB0_1469:
	s_andn2_saveexec_b64 s[0:1], s[4:5]
	s_cbranch_execz .LBB0_1487
	v_mov_b32_e32 v1, 0x26008
	ds_read_b32 v1, v1
	s_waitcnt lgkmcnt(0)
	v_readfirstlane_b32 s6, v1
	s_nop 0
	s_cmp_lg_u32 s6, 0
	s_cbranch_scc1 .Lxl_fast_0
	s_mov_b64 s[4:5], exec
	buffer_wbl2 sc1
	s_waitcnt lgkmcnt(0)
	s_waitcnt vmcnt(0)
	v_mbcnt_lo_u32_b32 v1, s4, 0
	v_mbcnt_hi_u32_b32 v1, s5, v1
	v_cmp_eq_u32_e32 vcc, 0, v1
	s_and_saveexec_b64 s[6:7], vcc
	s_cbranch_execz .LBB0_1472
	s_bcnt1_i32_b64 s0, s[4:5]
	v_mov_b32_e32 v2, s0
	v_readlane_b32 s0, v253, 44
	v_readlane_b32 s1, v253, 45
	s_nop 4
	global_atomic_add v2, v9, v2, s[0:1] sc0

; DEVI unsigned xb_add(unsigned* p, unsigned v) { return __hip_atomic_fetch_add(p, v, __ATOMIC_RELAXED, __HIP_MEMORY_SCOPE_AGENT); }
; DEVI void xcd_barrier(const XcdBarrier& b) {
;     ...
;             __builtin_amdgcn_fence(__ATOMIC_ACQUIRE, "agent");
;             xb_add(&bar[XB_XGEN(b.x)], 1u);
;             asm volatile("s_waitcnt vmcnt(0)" ::: "memory");
.Lxl_fast_0:
	s_waitcnt vmcnt(0)
	buffer_inv sc1
	global_atomic_add v[158:159], v161, off
	s_waitcnt vmcnt(0)
